# conv d-loops: one static priority raise for waves 4-7 (younger half) around the MFMA loop
# baseline (speedup 1.0000x reference)
.LBB0_985:
	v_add_u32_e32 v1, s6, v43
	v_cmp_gt_i32_e64 s[36:37], s82, v1
	s_or_b64 s[40:41], s[40:41], exec
	s_and_saveexec_b64 s[42:43], s[36:37]
	s_cbranch_execz .LBB0_984
	v_or_b32_e32 v0, v1, v44
	v_ashrrev_i32_e32 v54, s83, v0
	v_ashrrev_i32_e32 v0, s83, v1
	v_or_b32_e32 v2, 31, v1
	v_subrev_u32_e32 v0, s80, v0
	v_add_u32_e32 v0, 1, v0
	v_bitop3_b32 v35, v1, s84, v44 bitop3:0xc8
	v_ashrrev_i32_e32 v1, s83, v2
	v_max_i32_e32 v0, s85, v0
	v_min_i32_e32 v36, s81, v1
	v_mul_lo_u32 v1, v35, s79
	v_cmp_le_i32_e64 s[36:37], v0, v36
	v_add_u32_e32 v55, s24, v1
	v_lshlrev_b32_e32 v34, 6, v54
	s_and_saveexec_b64 s[6:7], s[36:37]
	s_xor_b64 s[46:47], exec, s[6:7]
	s_cbranch_execz .LBB0_990
	v_add_u32_e32 v37, -1, v0
	v_lshlrev_b32_e32 v1, 7, v0
	v_sub_u32_e32 v39, v54, v0
	v_lshlrev_b32_e32 v34, 6, v54
	v_lshlrev_b32_e32 v0, 6, v0
	v_mov_b32_e32 v16, 0
	v_sub_u32_e32 v38, v53, v1
	v_sub_u32_e32 v40, v34, v0
	s_mov_b64 s[50:51], 0
	v_mov_b32_e32 v17, v16
	v_mov_b32_e32 v18, v16
	v_mov_b32_e32 v19, v16
	v_mov_b32_e32 v20, v16
	v_mov_b32_e32 v21, v16
	v_mov_b32_e32 v22, v16
	v_mov_b32_e32 v23, v16
	v_mov_b32_e32 v24, v16
	v_mov_b32_e32 v25, v16
	v_mov_b32_e32 v26, v16
	v_mov_b32_e32 v27, v16
	v_mov_b32_e32 v28, v16
	v_mov_b32_e32 v29, v16
	v_mov_b32_e32 v30, v16
	v_mov_b32_e32 v31, v16
	v_mov_b32_e32 v0, v16
	v_mov_b32_e32 v1, v16
	v_mov_b32_e32 v2, v16
	v_mov_b32_e32 v3, v16
	v_mov_b32_e32 v4, v16
	v_mov_b32_e32 v5, v16
	v_mov_b32_e32 v6, v16
	v_mov_b32_e32 v7, v16
	v_mov_b32_e32 v8, v16
	v_mov_b32_e32 v9, v16
	v_mov_b32_e32 v10, v16
	v_mov_b32_e32 v11, v16
	v_mov_b32_e32 v12, v16
	v_mov_b32_e32 v13, v16
	v_mov_b32_e32 v14, v16
	v_mov_b32_e32 v15, v16
	v_cmp_lt_i32_e64 s[36:37], -1, v39
	v_cmp_gt_i32_e64 s[100:101], s80, v39
	s_nop 1
	s_and_b64 s[36:37], s[36:37], s[100:101]
	v_cndmask_b32_e64 v41, 0, v40, s[36:37]
	v_or_b32_e32 v41, v41, v45
	v_lshl_add_u32 v41, v41, 1, v55
	ds_read_b128 v[76:79], v38
	ds_read_b128 v[80:83], v38 offset:32
	ds_read_b128 v[84:87], v38 offset:64
	ds_read_b128 v[88:91], v38 offset:96
	ds_read_b128 v[108:111], v38 offset:128
	ds_read_b128 v[112:115], v38 offset:160
	ds_read_b128 v[92:95], v41
	ds_read_b128 v[96:99], v41 offset:32
	ds_read_b128 v[100:103], v41 offset:64
	ds_read_b128 v[104:107], v41 offset:96
	v_readfirstlane_b32 s101, v188
	s_nop 3
	s_lshr_b32 s101, s101, 8
	s_cmp_eq_u32 s101, 0
	s_cbranch_scc1 .Lconv_prio_0
	s_setprio 1
.Lconv_prio_0:
.Lconv_dloop_0:
	v_add_u32_e32 v38, 0xffffff80, v38
	v_add_u32_e32 v39, -1, v39
	v_subrev_u32_e32 v40, 64, v40
	v_add_u32_e32 v37, 1, v37
	v_max_i32_e32 v140, 0, v38
	v_cmp_lt_i32_e64 s[38:39], -1, v39
	v_cmp_gt_i32_e64 s[100:101], s80, v39
	s_nop 1
	s_and_b64 s[38:39], s[38:39], s[100:101]
	v_cndmask_b32_e64 v41, 0, v40, s[38:39]
	v_or_b32_e32 v41, v41, v45
	v_lshl_add_u32 v41, v41, 1, v55
	ds_read_b128 v[124:127], v41
	ds_read_b128 v[128:131], v41 offset:32
	ds_read_b128 v[132:135], v41 offset:64
	ds_read_b128 v[136:139], v41 offset:96
	ds_read_b128 v[116:119], v140 offset:64
	ds_read_b128 v[120:123], v140 offset:96
	s_waitcnt lgkmcnt(6)
	s_xor_b64 s[100:101], s[36:37], exec
	s_cbranch_scc0 .Lconv_dskip_0_0
	v_cndmask_b32_e64 v92, 0, v92, s[36:37]
	v_cndmask_b32_e64 v93, 0, v93, s[36:37]
	v_cndmask_b32_e64 v94, 0, v94, s[36:37]
	v_cndmask_b32_e64 v95, 0, v95, s[36:37]
	v_cndmask_b32_e64 v96, 0, v96, s[36:37]
	v_cndmask_b32_e64 v97, 0, v97, s[36:37]
	v_cndmask_b32_e64 v98, 0, v98, s[36:37]
	v_cndmask_b32_e64 v99, 0, v99, s[36:37]
	v_cndmask_b32_e64 v100, 0, v100, s[36:37]
	v_cndmask_b32_e64 v101, 0, v101, s[36:37]
	v_cndmask_b32_e64 v102, 0, v102, s[36:37]
	v_cndmask_b32_e64 v103, 0, v103, s[36:37]
	v_cndmask_b32_e64 v104, 0, v104, s[36:37]
	v_cndmask_b32_e64 v105, 0, v105, s[36:37]
	v_cndmask_b32_e64 v106, 0, v106, s[36:37]
	v_cndmask_b32_e64 v107, 0, v107, s[36:37]

.Lconv_ddone_0:
	s_setprio 0
	s_or_b64 exec, exec, s[50:51]

.LBB0_1099:
	v_add_u32_e32 v1, s6, v45
	v_cmp_gt_i32_e64 s[34:35], s77, v1
	s_or_b64 s[38:39], s[38:39], exec
	s_and_saveexec_b64 s[40:41], s[34:35]
	s_cbranch_execz .LBB0_1098
	v_or_b32_e32 v0, v1, v46
	v_ashrrev_i32_e32 v56, s78, v0
	v_ashrrev_i32_e32 v0, s78, v1
	v_or_b32_e32 v2, 31, v1
	v_subrev_u32_e32 v0, s65, v0
	v_add_u32_e32 v0, 1, v0
	v_bitop3_b32 v37, v1, s79, v46 bitop3:0xc8
	v_ashrrev_i32_e32 v1, s78, v2
	v_max_i32_e32 v0, s80, v0
	v_min_i32_e32 v38, s76, v1
	v_mul_lo_u32 v1, v37, s61
	v_cmp_le_i32_e64 s[34:35], v0, v38
	v_add_u32_e32 v57, s24, v1
	v_lshlrev_b32_e32 v36, 6, v56
	s_and_saveexec_b64 s[6:7], s[34:35]
	s_xor_b64 s[44:45], exec, s[6:7]
	s_cbranch_execz .LBB0_1104
	v_add_u32_e32 v39, -1, v0
	v_lshlrev_b32_e32 v1, 7, v0
	v_sub_u32_e32 v41, v56, v0
	v_lshlrev_b32_e32 v36, 6, v56
	v_lshlrev_b32_e32 v0, 6, v0
	v_mov_b32_e32 v16, 0
	v_sub_u32_e32 v40, v55, v1
	v_sub_u32_e32 v42, v36, v0
	s_mov_b64 s[46:47], 0
	v_mov_b32_e32 v17, v16
	v_mov_b32_e32 v18, v16
	v_mov_b32_e32 v19, v16
	v_mov_b32_e32 v20, v16
	v_mov_b32_e32 v21, v16
	v_mov_b32_e32 v22, v16
	v_mov_b32_e32 v23, v16
	v_mov_b32_e32 v24, v16
	v_mov_b32_e32 v25, v16
	v_mov_b32_e32 v26, v16
	v_mov_b32_e32 v27, v16
	v_mov_b32_e32 v28, v16
	v_mov_b32_e32 v29, v16
	v_mov_b32_e32 v30, v16
	v_mov_b32_e32 v31, v16
	v_mov_b32_e32 v0, v16
	v_mov_b32_e32 v1, v16
	v_mov_b32_e32 v2, v16
	v_mov_b32_e32 v3, v16
	v_mov_b32_e32 v4, v16
	v_mov_b32_e32 v5, v16
	v_mov_b32_e32 v6, v16
	v_mov_b32_e32 v7, v16
	v_mov_b32_e32 v8, v16
	v_mov_b32_e32 v9, v16
	v_mov_b32_e32 v10, v16
	v_mov_b32_e32 v11, v16
	v_mov_b32_e32 v12, v16
	v_mov_b32_e32 v13, v16
	v_mov_b32_e32 v14, v16
	v_mov_b32_e32 v15, v16
	v_cmp_lt_i32_e64 s[34:35], -1, v41
	v_cmp_gt_i32_e64 s[100:101], s65, v41
	s_nop 1
	s_and_b64 s[34:35], s[34:35], s[100:101]
	v_cndmask_b32_e64 v43, 0, v42, s[34:35]
	v_or_b32_e32 v43, v43, v47
	v_lshl_add_u32 v43, v43, 1, v57
	ds_read_b128 v[76:79], v40
	ds_read_b128 v[80:83], v40 offset:32
	ds_read_b128 v[84:87], v40 offset:64
	ds_read_b128 v[88:91], v40 offset:96
	ds_read_b128 v[108:111], v40 offset:128
	ds_read_b128 v[112:115], v40 offset:160
	ds_read_b128 v[92:95], v43
	ds_read_b128 v[96:99], v43 offset:32
	ds_read_b128 v[100:103], v43 offset:64
	ds_read_b128 v[104:107], v43 offset:96
	v_readfirstlane_b32 s101, v188
	s_nop 3
	s_lshr_b32 s101, s101, 8
	s_cmp_eq_u32 s101, 0
	s_cbranch_scc1 .Lconv_prio_1
	s_setprio 1
.Lconv_prio_1:
.Lconv_dloop_1:
	v_add_u32_e32 v40, 0xffffff80, v40
	v_add_u32_e32 v41, -1, v41
	v_subrev_u32_e32 v42, 64, v42
	v_add_u32_e32 v39, 1, v39
	v_max_i32_e32 v140, 0, v40
	v_cmp_lt_i32_e64 s[36:37], -1, v41
	v_cmp_gt_i32_e64 s[100:101], s65, v41
	s_nop 1
	s_and_b64 s[36:37], s[36:37], s[100:101]
	v_cndmask_b32_e64 v43, 0, v42, s[36:37]
	v_or_b32_e32 v43, v43, v47
	v_lshl_add_u32 v43, v43, 1, v57
	ds_read_b128 v[124:127], v43
	ds_read_b128 v[128:131], v43 offset:32
	ds_read_b128 v[132:135], v43 offset:64
	ds_read_b128 v[136:139], v43 offset:96
	ds_read_b128 v[116:119], v140 offset:64
	ds_read_b128 v[120:123], v140 offset:96
	s_waitcnt lgkmcnt(6)
	s_xor_b64 s[100:101], s[34:35], exec
	s_cbranch_scc0 .Lconv_dskip_1_0
	v_cndmask_b32_e64 v92, 0, v92, s[34:35]
	v_cndmask_b32_e64 v93, 0, v93, s[34:35]
	v_cndmask_b32_e64 v94, 0, v94, s[34:35]
	v_cndmask_b32_e64 v95, 0, v95, s[34:35]
	v_cndmask_b32_e64 v96, 0, v96, s[34:35]
	v_cndmask_b32_e64 v97, 0, v97, s[34:35]
	v_cndmask_b32_e64 v98, 0, v98, s[34:35]
	v_cndmask_b32_e64 v99, 0, v99, s[34:35]
	v_cndmask_b32_e64 v100, 0, v100, s[34:35]
	v_cndmask_b32_e64 v101, 0, v101, s[34:35]
	v_cndmask_b32_e64 v102, 0, v102, s[34:35]
	v_cndmask_b32_e64 v103, 0, v103, s[34:35]
	v_cndmask_b32_e64 v104, 0, v104, s[34:35]
	v_cndmask_b32_e64 v105, 0, v105, s[34:35]
	v_cndmask_b32_e64 v106, 0, v106, s[34:35]
	v_cndmask_b32_e64 v107, 0, v107, s[34:35]

.Lconv_ddone_1:
	s_setprio 0
	s_or_b64 exec, exec, s[46:47]
